# QK K-fragment prefetch depth reduced from 12 to 4 (LDS queue pressure); fast pooling; prologue fill
# speedup vs baseline: 1.0136x; 1.0136x over previous
; #define LAS __attribute__((address_space(3)))
; __device__ __forceinline__ void compute_a(LAS unsigned char* lds, const UD& x, const bf16x8 (&qr)[4], int wid, int lane, u32x4 (&pw)[10], float& mx_o, float& l_o) {
;     const int r32 = lane & 31, hi = lane >> 5;
;     int d, L, cls, t0, sbase; wave_geo(x, wid, d, L, cls, t0, sbase);
;     f32x16 s[5];
; #pragma unroll
;     for (int ht = 0; ht < 5; ++ht) {
;         const LAS unsigned char* kb = lds + L_K + hi * KCS + (sbase + 32 * ht + r32) * 16;
;         f32x16 a = {};
; #pragma unroll
;         for (int d0 = 0; d0 < 4; ++d0) { const bf16x8 kf = *(const LAS bf16x8*)(kb + d0 * 2 * KCS); a = __builtin_amdgcn_mfma_f32_32x32x16_bf16(kf, qr[d0], a, 0, 0, 0); }
;         s[ht] = a;
;     }
;     {
;         const int dq = r32 - 4 * hi;
; #pragma unroll
;         for (int r = 0; r < 16; ++r) { const int cr = (r & 3) + 8 * (r >> 2); s[0][r] = (cr >= dq) ? s[0][r] : -INFINITY; s[4][r] = (cr <= dq) ? s[4][r] : -INFINITY; }
;         if (t0 < 64) {
; #pragma unroll
;             for (int r = 0; r < 16; ++r) s[0][r] = -INFINITY;
;             if (t0 < 32) {
; #pragma unroll
;                 for (int r = 0; r < 16; ++r) s[1][r] = -INFINITY;
;             }
.LBB0_634:
	s_ashr_i32 s1, s18, 4
	s_mul_hi_i32 s0, s1, 0x2aaaaaab
	s_lshr_b32 s4, s0, 31
	s_ashr_i32 s0, s0, 1
	s_add_i32 s0, s0, s4
	s_mul_i32 s4, s0, 12
	s_bfe_u32 s13, s18, 0x10003
	s_sub_i32 s20, s1, s4
	s_cmp_eq_u32 s13, 0
	s_cselect_b64 s[22:23], -1, 0
	s_and_b64 s[16:17], s[22:23], exec
	s_cselect_b32 s11, 2, 4
	s_cselect_b32 s21, s45, s9
	s_cselect_b32 s12, s10, s8
	s_ashr_i32 s1, s0, 31
	s_lshl_b64 s[16:17], s[0:1], 23
	v_readlane_b32 s4, v252, 1
	v_cndmask_b32_e64 v0, v214, v194, s[22:23]
	v_readlane_b32 s5, v252, 2
	s_add_u32 s16, s4, s16
	v_or_b32_e32 v2, s12, v160
	s_addc_u32 s17, s5, s17
	s_lshl_b64 s[46:47], s[0:1], 11
	v_ashrrev_i32_e32 v3, 31, v2
	v_ashrrev_i32_e32 v1, 31, v0
	v_lshlrev_b64 v[2:3], s11, v[2:3]
	v_lshl_add_u64 v[150:151], s[46:47], 0, v[0:1]
	v_lshl_add_u64 v[152:153], v[150:151], 0, v[2:3]
	v_mov_b64_e32 v[0:1], s[16:17]
	v_mad_u64_u32 v[0:1], s[16:17], v152, s40, v[0:1]
	s_lshl_b32 s16, s20, 6
	v_mad_i32_i24 v1, v153, s40, v1
	s_ashr_i32 s17, s16, 31
	v_lshl_add_u64 v[0:1], s[16:17], 1, v[0:1]
	v_mov_b32_e32 v147, v81
	v_lshl_add_u64 v[0:1], v[0:1], 0, v[146:147]
	s_mov_b64 s[4:5], 0xc000000
	s_brev_b32 s1, 48
	v_lshl_add_u64 v[2:3], v[0:1], 0, s[4:5]
	v_add_co_u32_e32 v0, vcc, s1, v0
	s_cmp_gt_i32 s12, 63
	s_nop 0
	v_addc_co_u32_e32 v1, vcc, 0, v1, vcc
	global_load_dwordx4 v[48:51], v[0:1], off
	global_load_dwordx4 v[234:237], v[2:3], off offset:32
	global_load_dwordx4 v[242:245], v[2:3], off offset:64
	global_load_dwordx4 v[132:135], v[2:3], off offset:96
	v_or_b32_e32 v0, s21, v160
	v_lshl_add_u32 v80, v0, 4, v161
	s_waitcnt vmcnt(12)
	ds_write_b128 v215, v[84:87]
	ds_write_b128 v216, v[88:91]
	ds_write_b128 v217, v[92:95]
	ds_write_b128 v218, v[96:99]
	ds_write_b128 v219, v[100:103]
	ds_write_b128 v220, v[104:107]
	ds_write_b128 v221, v[108:111]
	ds_write_b128 v222, v[112:115]
	s_waitcnt vmcnt(11)
	ds_write_b128 v223, v[116:119]
	s_waitcnt vmcnt(10)
	ds_write_b128 v224, v[120:123]
	s_waitcnt vmcnt(5)
	ds_write_b128 v225, v[124:127]
	s_waitcnt vmcnt(4)
	ds_write_b128 v226, v[128:131]
	ds_write_b128 v227, v[238:241]
	ds_write_b128 v228, v[238:241]
	s_waitcnt lgkmcnt(0)
	s_barrier
	ds_read_b128 v[84:87], v80
	ds_read_b128 v[88:91], v80 offset:14368
	ds_read_b128 v[92:95], v80 offset:28736
	ds_read_b128 v[96:99], v80 offset:43104
	s_waitcnt vmcnt(3) lgkmcnt(3)
	v_mfma_f32_32x32x16_bf16 v[64:79], v[84:87], v[48:51], 0
	ds_read_b128 v[84:87], v80 offset:512
	s_waitcnt vmcnt(2) lgkmcnt(3)
	v_mfma_f32_32x32x16_bf16 v[64:79], v[88:91], v[234:237], v[64:79]
	ds_read_b128 v[88:91], v80 offset:14880
	s_waitcnt vmcnt(1) lgkmcnt(3)
	v_mfma_f32_32x32x16_bf16 v[64:79], v[92:95], v[242:245], v[64:79]
	ds_read_b128 v[92:95], v80 offset:29248
	s_waitcnt vmcnt(0) lgkmcnt(3)
	v_mfma_f32_32x32x16_bf16 v[64:79], v[96:99], v[132:135], v[64:79]
	ds_read_b128 v[96:99], v80 offset:43616
	s_waitcnt lgkmcnt(3)
	v_mfma_f32_32x32x16_bf16 v[32:47], v[84:87], v[48:51], 0
	ds_read_b128 v[84:87], v80 offset:1024
	s_waitcnt lgkmcnt(3)
	v_mfma_f32_32x32x16_bf16 v[32:47], v[88:91], v[234:237], v[32:47]
	ds_read_b128 v[88:91], v80 offset:15392
	s_waitcnt lgkmcnt(3)
	v_mfma_f32_32x32x16_bf16 v[32:47], v[92:95], v[242:245], v[32:47]
	ds_read_b128 v[92:95], v80 offset:29760
	s_waitcnt lgkmcnt(3)
	v_mfma_f32_32x32x16_bf16 v[32:47], v[96:99], v[132:135], v[32:47]
	ds_read_b128 v[96:99], v80 offset:44128
	s_waitcnt lgkmcnt(3)
	v_mfma_f32_32x32x16_bf16 v[16:31], v[84:87], v[48:51], 0
	ds_read_b128 v[84:87], v80 offset:1536
	s_waitcnt lgkmcnt(3)
	v_mfma_f32_32x32x16_bf16 v[16:31], v[88:91], v[234:237], v[16:31]
	ds_read_b128 v[88:91], v80 offset:15904
	s_waitcnt lgkmcnt(3)
	v_mfma_f32_32x32x16_bf16 v[16:31], v[92:95], v[242:245], v[16:31]
	ds_read_b128 v[92:95], v80 offset:30272
	s_waitcnt lgkmcnt(3)
	v_mfma_f32_32x32x16_bf16 v[16:31], v[96:99], v[132:135], v[16:31]
	ds_read_b128 v[96:99], v80 offset:44640
	s_waitcnt lgkmcnt(3)
	v_mfma_f32_32x32x16_bf16 v[0:15], v[84:87], v[48:51], 0
	ds_read_b128 v[84:87], v80 offset:2048
	s_waitcnt lgkmcnt(3)
	v_mfma_f32_32x32x16_bf16 v[0:15], v[88:91], v[234:237], v[0:15]
	ds_read_b128 v[88:91], v80 offset:16416
	s_waitcnt lgkmcnt(3)
	v_mfma_f32_32x32x16_bf16 v[0:15], v[92:95], v[242:245], v[0:15]
	ds_read_b128 v[92:95], v80 offset:30784
	s_waitcnt lgkmcnt(3)
	v_mfma_f32_32x32x16_bf16 v[0:15], v[96:99], v[132:135], v[0:15]
	ds_read_b128 v[96:99], v80 offset:45152
	s_waitcnt lgkmcnt(3)
	v_mfma_f32_32x32x16_bf16 v[48:63], v[84:87], v[48:51], 0
	s_waitcnt lgkmcnt(2)
	v_mfma_f32_32x32x16_bf16 v[48:63], v[88:91], v[234:237], v[48:63]
	s_waitcnt lgkmcnt(1)
	v_mfma_f32_32x32x16_bf16 v[48:63], v[92:95], v[242:245], v[48:63]
	s_waitcnt lgkmcnt(0)
	v_mfma_f32_32x32x16_bf16 v[48:63], v[96:99], v[132:135], v[48:63]
	s_cbranch_scc1 .LBB0_638
	s_cmp_gt_i32 s12, 31
	s_cbranch_scc1 .LBB0_637
	v_mov_b32_e32 v47, 0xff800000
	v_mov_b32_e32 v46, v47
	v_mov_b32_e32 v45, v47
	v_mov_b32_e32 v44, v47
	v_mov_b32_e32 v43, v47
	v_mov_b32_e32 v42, v47
	v_mov_b32_e32 v41, v47
	v_mov_b32_e32 v40, v47
	v_mov_b32_e32 v39, v47
	v_mov_b32_e32 v38, v47
	v_mov_b32_e32 v37, v47
	v_mov_b32_e32 v36, v47
	v_mov_b32_e32 v35, v47
	v_mov_b32_e32 v34, v47
	v_mov_b32_e32 v33, v47
	v_mov_b32_e32 v32, v47

; #define LAS __attribute__((address_space(3)))
; __device__ __forceinline__ void store_kv(LAS unsigned char* lds, const u32x4 (&val)[14], int tid) {
; #pragma unroll
;     for (int i = 0; i < 14; ++i) {
;         const int piece = tid + 512 * i, slot = piece >> 4, sub = piece & 15;
;         const int off = (sub < 8) ? (L_K + sub * KCS + slot * 16) : (L_V + ((sub - 8) >> 2) * VDS + slot * 64 + ((sub - 8) & 3) * 16);
;         *(LAS u32x4*)(lds + off) = val[i];
;     }
; }
; __device__ __forceinline__ void wave_geo(const UD& x, int wid, int& d, int& L, int& cls, int& t0, int& sbase) {
;     const int br = x.br, u = x.u; d = (br == 0) ? 1 : (br == 1) ? 4 : 16; L = SEQ / d;
;     if (br < 2) { const int T0 = (br == 0) ? 256 * u : 256 * (u & 1); cls = (br == 0) ? 0 : (u >> 1); t0 = T0 + 32 * wid; sbase = 32 * wid; }
;     else { const int hw = wid >> 2; cls = 2 * u + hw; t0 = 32 * (wid & 3); sbase = 192 * hw + 32 * (wid & 3); }
; }
; __device__ __forceinline__ void load_q(bf16x8 (&qr)[4], const UD& x, const unsigned char* ws, int wid, int r32, int hi) {
;     int d, L, cls, t0, sbase; wave_geo(x, wid, d, L, cls, t0, sbase);
;     const bf16_t* Qb = (const bf16_t*)(ws + off_q(x.b));
;     const size_t qtok = (size_t)x.b * SEQ + (size_t)(t0 + r32) * d + cls;
; #pragma unroll
;     for (int d0 = 0; d0 < 4; ++d0) qr[d0] = *(const bf16x8*)(Qb + qtok * AW + x.h * HD + d0 * 16 + hi * 8);
; }
; __device__ __forceinline__ void compute_a(LAS unsigned char* lds, const UD& x, const bf16x8 (&qr)[4], int wid, int lane, u32x4 (&pw)[10], float& mx_o, float& l_o) {
;     const int r32 = lane & 31, hi = lane >> 5;
;     int d, L, cls, t0, sbase; wave_geo(x, wid, d, L, cls, t0, sbase);
;     f32x16 s[5];
; #pragma unroll
;     for (int ht = 0; ht < 5; ++ht) {
;         const LAS unsigned char* kb = lds + L_K + hi * KCS + (sbase + 32 * ht + r32) * 16;
;         f32x16 a = {};
; #pragma unroll
;         for (int d0 = 0; d0 < 4; ++d0) { const bf16x8 kf = *(const LAS bf16x8*)(kb + d0 * 2 * KCS); a = __builtin_amdgcn_mfma_f32_32x32x16_bf16(kf, qr[d0], a, 0, 0, 0); }
;         s[ht] = a;
;     }
.LBB0_903:
	s_ashr_i32 s1, s18, 3
	s_mul_hi_i32 s0, s1, 0x2aaaaaab
	s_lshr_b32 s14, s0, 31
	s_ashr_i32 s0, s0, 1
	s_add_i32 s0, s0, s14
	s_mul_i32 s14, s0, 12
	s_sub_i32 s22, s1, s14
	s_lshl_b32 s1, s18, 8
	s_and_b32 s21, s1, 0x700
	s_ashr_i32 s1, s0, 31
	s_lshl_b64 s[14:15], s[0:1], 23
	v_readlane_b32 s16, v252, 1
	v_readlane_b32 s17, v252, 2
	s_add_u32 s16, s16, s14
	v_add_u32_e32 v0, s21, v150
	s_addc_u32 s17, s17, s15
	s_lshl_b64 s[14:15], s[0:1], 11
	v_ashrrev_i32_e32 v1, 31, v0
	v_lshl_add_u64 v[0:1], s[14:15], 0, v[0:1]
	v_mov_b64_e32 v[2:3], s[16:17]
	v_mad_u64_u32 v[2:3], s[16:17], v0, s40, v[2:3]
	s_lshl_b32 s16, s22, 6
	v_mad_i32_i24 v3, v1, s40, v3
	s_ashr_i32 s17, s16, 31
	v_lshl_add_u64 v[0:1], s[16:17], 1, v[2:3]
	v_mov_b32_e32 v143, v81
	v_lshl_add_u64 v[0:1], v[0:1], 0, v[142:143]
	s_mov_b64 s[24:25], 0xc000000
	s_brev_b32 s19, 48
	v_lshl_add_u64 v[2:3], v[0:1], 0, s[24:25]
	v_add_co_u32_e32 v0, vcc, s19, v0
	s_add_i32 s20, s21, s80
	s_nop 0
	v_addc_co_u32_e32 v1, vcc, 0, v1, vcc
	global_load_dwordx4 v[48:51], v[0:1], off
	global_load_dwordx4 v[232:235], v[2:3], off offset:32
	global_load_dwordx4 v[242:245], v[2:3], off offset:64
	global_load_dwordx4 v[246:249], v[2:3], off offset:96
	s_waitcnt vmcnt(4)
	ds_write_b128 v214, v[84:87]
	ds_write_b128 v215, v[88:91]
	ds_write_b128 v216, v[92:95]
	ds_write_b128 v217, v[96:99]
	ds_write_b128 v218, v[100:103]
	ds_write_b128 v219, v[104:107]
	ds_write_b128 v220, v[108:111]
	ds_write_b128 v221, v[112:115]
	ds_write_b128 v222, v[116:119]
	ds_write_b128 v223, v[120:123]
	ds_write_b128 v224, v[124:127]
	ds_write_b128 v225, v[128:131]
	ds_write_b128 v226, v[238:241]
	ds_write_b128 v227, v[238:241]
	s_waitcnt lgkmcnt(0)
	s_barrier
	ds_read_b128 v[84:87], v228
	ds_read_b128 v[88:91], v228 offset:14368
	ds_read_b128 v[92:95], v228 offset:28736
	ds_read_b128 v[96:99], v228 offset:43104
	s_cmp_gt_i32 s20, 63
	s_waitcnt vmcnt(3) lgkmcnt(3)
	v_mfma_f32_32x32x16_bf16 v[64:79], v[84:87], v[48:51], 0
	ds_read_b128 v[84:87], v228 offset:512
	s_waitcnt vmcnt(2) lgkmcnt(3)
	v_mfma_f32_32x32x16_bf16 v[64:79], v[88:91], v[232:235], v[64:79]
	ds_read_b128 v[88:91], v228 offset:14880
	s_waitcnt vmcnt(1) lgkmcnt(3)
	v_mfma_f32_32x32x16_bf16 v[64:79], v[92:95], v[242:245], v[64:79]
	ds_read_b128 v[92:95], v228 offset:29248
	s_waitcnt vmcnt(0) lgkmcnt(3)
	v_mfma_f32_32x32x16_bf16 v[64:79], v[96:99], v[246:249], v[64:79]
	ds_read_b128 v[96:99], v228 offset:43616
	s_waitcnt lgkmcnt(3)
	v_mfma_f32_32x32x16_bf16 v[32:47], v[84:87], v[48:51], 0
	ds_read_b128 v[84:87], v228 offset:1024
	s_waitcnt lgkmcnt(3)
	v_mfma_f32_32x32x16_bf16 v[32:47], v[88:91], v[232:235], v[32:47]
	ds_read_b128 v[88:91], v228 offset:15392
	s_waitcnt lgkmcnt(3)
	v_mfma_f32_32x32x16_bf16 v[32:47], v[92:95], v[242:245], v[32:47]
	ds_read_b128 v[92:95], v228 offset:29760
	s_waitcnt lgkmcnt(3)
	v_mfma_f32_32x32x16_bf16 v[32:47], v[96:99], v[246:249], v[32:47]
	ds_read_b128 v[96:99], v228 offset:44128
	s_waitcnt lgkmcnt(3)
	v_mfma_f32_32x32x16_bf16 v[16:31], v[84:87], v[48:51], 0
	ds_read_b128 v[84:87], v228 offset:1536
	s_waitcnt lgkmcnt(3)
	v_mfma_f32_32x32x16_bf16 v[16:31], v[88:91], v[232:235], v[16:31]
	ds_read_b128 v[88:91], v228 offset:15904
	s_waitcnt lgkmcnt(3)
	v_mfma_f32_32x32x16_bf16 v[16:31], v[92:95], v[242:245], v[16:31]
	ds_read_b128 v[92:95], v228 offset:30272
	s_waitcnt lgkmcnt(3)
	v_mfma_f32_32x32x16_bf16 v[16:31], v[96:99], v[246:249], v[16:31]
	ds_read_b128 v[96:99], v228 offset:44640
	s_waitcnt lgkmcnt(3)
	v_mfma_f32_32x32x16_bf16 v[0:15], v[84:87], v[48:51], 0
	ds_read_b128 v[84:87], v228 offset:2048
	s_waitcnt lgkmcnt(3)
	v_mfma_f32_32x32x16_bf16 v[0:15], v[88:91], v[232:235], v[0:15]
	ds_read_b128 v[88:91], v228 offset:16416
	s_waitcnt lgkmcnt(3)
	v_mfma_f32_32x32x16_bf16 v[0:15], v[92:95], v[242:245], v[0:15]
	ds_read_b128 v[92:95], v228 offset:30784
	s_waitcnt lgkmcnt(3)
	v_mfma_f32_32x32x16_bf16 v[0:15], v[96:99], v[246:249], v[0:15]
	ds_read_b128 v[96:99], v228 offset:45152
	s_waitcnt lgkmcnt(3)
	v_mfma_f32_32x32x16_bf16 v[48:63], v[84:87], v[48:51], 0
	s_waitcnt lgkmcnt(2)
	v_mfma_f32_32x32x16_bf16 v[48:63], v[88:91], v[232:235], v[48:63]
	s_waitcnt lgkmcnt(1)
	v_mfma_f32_32x32x16_bf16 v[48:63], v[92:95], v[242:245], v[48:63]
	s_waitcnt lgkmcnt(0)
	v_mfma_f32_32x32x16_bf16 v[48:63], v[96:99], v[246:249], v[48:63]
	s_cbranch_scc1 .LBB0_908
	s_cmp_gt_i32 s20, 31
	s_cbranch_scc1 .LBB0_906
	v_mov_b32_e32 v47, 0xff800000
	v_mov_b32_e32 v46, v47
	v_mov_b32_e32 v45, v47
	v_mov_b32_e32 v44, v47
	v_mov_b32_e32 v43, v47
	v_mov_b32_e32 v42, v47
	v_mov_b32_e32 v41, v47
	v_mov_b32_e32 v40, v47
	v_mov_b32_e32 v39, v47
	v_mov_b32_e32 v38, v47
	v_mov_b32_e32 v37, v47
	v_mov_b32_e32 v36, v47
	v_mov_b32_e32 v35, v47
	v_mov_b32_e32 v34, v47
	v_mov_b32_e32 v33, v47
	v_mov_b32_e32 v32, v47
